# v16 + attention: QK^T by key block, row max of block 0 in block 1's MFMA gaps
# baseline (speedup 1.0000x reference)
.Latt1_noload_a:
	ds_read_b128 v[242:245], v250 offset:13888
	v_exp_f32_e32 v88, v88
	v_exp_f32_e32 v89, v89
	v_exp_f32_e32 v90, v90
	s_waitcnt lgkmcnt(10)
	v_mfma_f32_32x32x16_bf16 v[32:47], v[192:195], v[80:83], v[32:47]
	ds_read_b128 v[246:249], v250 offset:96
	v_exp_f32_e32 v91, v91
	v_exp_f32_e32 v92, v92
	v_exp_f32_e32 v93, v93
	v_add_f32_e32 v145, v145, v88
	v_add_f32_e32 v146, v146, v89
	s_waitcnt lgkmcnt(10)
	v_mfma_f32_32x32x16_bf16 v[16:31], v[196:199], v[80:83], v[16:31]
	ds_read_b128 v[180:183], v250 offset:4704
	v_exp_f32_e32 v94, v94
	v_exp_f32_e32 v95, v95
	v_add_f32_e32 v150, v150, v90
	v_add_f32_e32 v151, v151, v91
	v_add_f32_e32 v145, v145, v92
	v_add_f32_e32 v146, v146, v93
	s_waitcnt lgkmcnt(10)
	v_mfma_f32_32x32x16_bf16 v[0:15], v[200:203], v[80:83], v[0:15]
	ds_read_b128 v[184:187], v250 offset:9312
	v_cvt_pk_bf16_f32 v88, v88, v89
	v_cvt_pk_bf16_f32 v89, v90, v91
	v_cvt_pk_bf16_f32 v90, v92, v93
	v_cvt_pk_bf16_f32 v91, v94, v95
	v_add_f32_e32 v150, v150, v94
	v_add_f32_e32 v151, v151, v95
	s_waitcnt lgkmcnt(10)
	v_mfma_f32_32x32x16_bf16 v[48:63], v[204:207], v[88:91], v[48:63]
	ds_read_b128 v[188:191], v250 offset:13920
	v_exp_f32_e32 v96, v96
	v_exp_f32_e32 v97, v97
	v_exp_f32_e32 v98, v98
	s_waitcnt lgkmcnt(10)
	v_mfma_f32_32x32x16_bf16 v[32:47], v[218:221], v[88:91], v[32:47]
	v_exp_f32_e32 v99, v99
	v_exp_f32_e32 v100, v100
	v_exp_f32_e32 v101, v101
	v_add_f32_e32 v145, v145, v96
	v_add_f32_e32 v146, v146, v97
	s_waitcnt lgkmcnt(9)
	v_mfma_f32_32x32x16_bf16 v[16:31], v[222:225], v[88:91], v[16:31]
	v_exp_f32_e32 v102, v102
	v_exp_f32_e32 v103, v103
	v_add_f32_e32 v150, v150, v98
	v_add_f32_e32 v151, v151, v99
	v_add_f32_e32 v145, v145, v100
	v_add_f32_e32 v146, v146, v101
	s_waitcnt lgkmcnt(8)
	v_mfma_f32_32x32x16_bf16 v[0:15], v[226:229], v[88:91], v[0:15]
	v_cvt_pk_bf16_f32 v96, v96, v97
	v_cvt_pk_bf16_f32 v97, v98, v99
	v_cvt_pk_bf16_f32 v98, v100, v101
	v_cvt_pk_bf16_f32 v99, v102, v103
	v_add_f32_e32 v150, v150, v102
	v_add_f32_e32 v151, v151, v103
	s_barrier
	ds_read_b128 v[192:195], v173
	ds_read_b128 v[200:203], v173 offset:32
	ds_read_b128 v[218:221], v173 offset:64
	ds_read_b128 v[226:229], v173 offset:96
	ds_read_b128 v[196:199], v173 offset:8704
	ds_read_b128 v[204:207], v173 offset:8736
	ds_read_b128 v[222:225], v173 offset:8768
	s_waitcnt lgkmcnt(14)
	v_mfma_f32_32x32x16_bf16 v[48:63], v[230:233], v[96:99], v[48:63]
	ds_read_b128 v[230:233], v173 offset:8800
	v_exp_f32_e32 v104, v104
	v_exp_f32_e32 v105, v105
	v_exp_f32_e32 v106, v106
	s_waitcnt lgkmcnt(14)
	v_mfma_f32_32x32x16_bf16 v[32:47], v[234:237], v[96:99], v[32:47]
	v_exp_f32_e32 v107, v107
	v_exp_f32_e32 v108, v108
	v_exp_f32_e32 v109, v109
	v_add_f32_e32 v145, v145, v104
	v_add_f32_e32 v146, v146, v105
	s_waitcnt lgkmcnt(13)
	v_mfma_f32_32x32x16_bf16 v[16:31], v[238:241], v[96:99], v[16:31]
	v_exp_f32_e32 v110, v110
	v_exp_f32_e32 v111, v111
	v_add_f32_e32 v150, v150, v106
	v_add_f32_e32 v151, v151, v107
	v_add_f32_e32 v145, v145, v108
	v_add_f32_e32 v146, v146, v109
	s_waitcnt lgkmcnt(12)
	v_mfma_f32_32x32x16_bf16 v[0:15], v[242:245], v[96:99], v[0:15]
	v_cvt_pk_bf16_f32 v104, v104, v105
	v_cvt_pk_bf16_f32 v105, v106, v107
	v_cvt_pk_bf16_f32 v106, v108, v109
	v_cvt_pk_bf16_f32 v107, v110, v111
	v_add_f32_e32 v150, v150, v110
	v_add_f32_e32 v151, v151, v111
	s_waitcnt lgkmcnt(11)
	v_mfma_f32_32x32x16_bf16 v[48:63], v[246:249], v[104:107], v[48:63]
	v_add_f32_e32 v145, v145, v146
	s_waitcnt lgkmcnt(10)
	v_mfma_f32_32x32x16_bf16 v[32:47], v[180:183], v[104:107], v[32:47]
	v_add_f32_e32 v150, v150, v151
	s_waitcnt lgkmcnt(9)
	v_mfma_f32_32x32x16_bf16 v[16:31], v[184:187], v[104:107], v[16:31]
	v_add_f32_e32 v145, v145, v150
	s_waitcnt lgkmcnt(8)
	v_mfma_f32_32x32x16_bf16 v[0:15], v[188:191], v[104:107], v[0:15]
	v_add_f32_e32 v158, v158, v145
	s_branch .Latt1_qk

.Latt1_noload_b:
	ds_read_b128 v[242:245], v250 offset:13888
	s_waitcnt lgkmcnt(10)
	v_mfma_f32_32x32x16_bf16 v[32:47], v[192:195], v[80:83], v[32:47]
	ds_read_b128 v[246:249], v250 offset:96
	s_waitcnt lgkmcnt(10)
	v_mfma_f32_32x32x16_bf16 v[16:31], v[196:199], v[80:83], v[16:31]
	ds_read_b128 v[180:183], v250 offset:4704
	s_waitcnt lgkmcnt(10)
	v_mfma_f32_32x32x16_bf16 v[0:15], v[200:203], v[80:83], v[0:15]
	ds_read_b128 v[184:187], v250 offset:9312
	s_waitcnt lgkmcnt(10)
	v_mfma_f32_32x32x16_bf16 v[48:63], v[204:207], v[88:91], v[48:63]
	ds_read_b128 v[188:191], v250 offset:13920
	s_waitcnt lgkmcnt(10)
	v_mfma_f32_32x32x16_bf16 v[32:47], v[218:221], v[88:91], v[32:47]
	s_waitcnt lgkmcnt(9)
	v_mfma_f32_32x32x16_bf16 v[16:31], v[222:225], v[88:91], v[16:31]
	s_waitcnt lgkmcnt(8)
	v_mfma_f32_32x32x16_bf16 v[0:15], v[226:229], v[88:91], v[0:15]
	s_barrier
	ds_read_b128 v[192:195], v173
	ds_read_b128 v[200:203], v173 offset:32
	ds_read_b128 v[218:221], v173 offset:64
	ds_read_b128 v[226:229], v173 offset:96
	ds_read_b128 v[196:199], v173 offset:8704
	ds_read_b128 v[204:207], v173 offset:8736
	ds_read_b128 v[222:225], v173 offset:8768
	s_waitcnt lgkmcnt(14)
	v_mfma_f32_32x32x16_bf16 v[48:63], v[230:233], v[84:87], v[48:63]
	ds_read_b128 v[230:233], v173 offset:8800
	s_waitcnt lgkmcnt(14)
	v_mfma_f32_32x32x16_bf16 v[32:47], v[234:237], v[84:87], v[32:47]
	s_waitcnt lgkmcnt(13)
	v_mfma_f32_32x32x16_bf16 v[16:31], v[238:241], v[84:87], v[16:31]
	s_waitcnt lgkmcnt(12)
	v_mfma_f32_32x32x16_bf16 v[0:15], v[242:245], v[84:87], v[0:15]
	s_waitcnt lgkmcnt(11)
	v_mfma_f32_32x32x16_bf16 v[48:63], v[246:249], v[92:95], v[48:63]
	s_waitcnt lgkmcnt(10)
	v_mfma_f32_32x32x16_bf16 v[32:47], v[180:183], v[92:95], v[32:47]
	s_waitcnt lgkmcnt(9)
	v_mfma_f32_32x32x16_bf16 v[16:31], v[184:187], v[92:95], v[16:31]
	s_waitcnt lgkmcnt(8)
	v_mfma_f32_32x32x16_bf16 v[0:15], v[188:191], v[92:95], v[0:15]
.Latt1_qk:
	s_waitcnt lgkmcnt(7)
	v_mfma_f32_32x32x16_bf16 v[80:95], v[192:195], v[112:115], v[64:79]
	s_waitcnt lgkmcnt(6)
	v_mfma_f32_32x32x16_bf16 v[80:95], v[200:203], v[116:119], v[80:95]
	s_waitcnt lgkmcnt(5)
	v_mfma_f32_32x32x16_bf16 v[80:95], v[218:221], v[120:123], v[80:95]
	s_waitcnt lgkmcnt(4)
	v_mfma_f32_32x32x16_bf16 v[80:95], v[226:229], v[124:127], v[80:95]
	s_waitcnt lgkmcnt(3)
	v_mfma_f32_32x32x16_bf16 v[96:111], v[196:199], v[112:115], v[64:79]
	s_waitcnt lgkmcnt(2)
	v_mfma_f32_32x32x16_bf16 v[96:111], v[204:207], v[116:119], v[96:111]
	s_nop 3
	v_max3_f32 v145, v80, v81, v82
	v_max3_f32 v145, v145, v83, v84
	v_max3_f32 v145, v145, v85, v86
	s_waitcnt lgkmcnt(1)
	v_mfma_f32_32x32x16_bf16 v[96:111], v[222:225], v[120:123], v[96:111]
	v_max3_f32 v145, v145, v87, v88
	v_max3_f32 v145, v145, v89, v90
	v_max3_f32 v145, v145, v91, v92
	v_max3_f32 v145, v145, v93, v94
	s_waitcnt lgkmcnt(0)
	v_mfma_f32_32x32x16_bf16 v[96:111], v[230:233], v[124:127], v[96:111]
	s_add_i32 s2, s19, 1
	s_cmp_lg_u32 s19, 2
	s_cselect_b32 s2, s2, 0
	s_add_i32 s17, s17, 64
	s_mov_b64 s[22:23], 0x80
	s_add_i32 s18, s18, 1
	v_lshl_add_u64 v[162:163], v[162:163], 0, s[22:23]
	v_lshl_add_u64 v[164:165], v[164:165], 0, s[22:23]
	s_nop 5
	v_max3_f32 v146, v96, v97, v98
	v_max3_f32 v146, v146, v99, v100
	v_max3_f32 v146, v146, v101, v102
	v_max3_f32 v146, v146, v103, v104
	v_max3_f32 v146, v146, v105, v106
	v_max3_f32 v146, v146, v107, v108
	v_max3_f32 v146, v146, v109, v110
	v_max3_f32 v145, v145, v95, v111
	v_max_f32_e32 v145, v145, v146
	v_cmp_lt_f32_e32 vcc, 0x41000000, v145
	s_cbranch_vccz .Latt1_nors
	ds_bpermute_b32 v146, v209, v145
	s_waitcnt lgkmcnt(0)
	v_max_f32_e32 v146, v145, v146
	v_cmp_lt_f32_e32 vcc, 0x41000000, v146
	s_nop 0
	s_nop 0
	v_cndmask_b32_e32 v146, 0, v146, vcc
	v_exp_f32_e64 v150, -v146
	v_add_f32_e32 v159, v159, v146
	v_xor_b32_e32 v64, 0x80000000, v159
	v_mov_b32_e32 v65, v64
	v_mov_b32_e32 v66, v64
	v_mov_b32_e32 v67, v64
	v_mov_b32_e32 v68, v64
	v_mov_b32_e32 v69, v64
	v_mov_b32_e32 v70, v64
	v_mov_b32_e32 v71, v64
	v_mov_b32_e32 v72, v64
	v_mov_b32_e32 v73, v64
	v_mov_b32_e32 v74, v64
	v_mov_b32_e32 v75, v64
	v_mov_b32_e32 v76, v64
	v_mov_b32_e32 v77, v64
	v_mov_b32_e32 v78, v64
	v_mov_b32_e32 v79, v64
	v_mul_f32_e32 v158, v158, v150
	v_pk_mul_f32 v[14:15], v[14:15], v[150:151] op_sel_hi:[1,0]
	v_pk_mul_f32 v[12:13], v[12:13], v[150:151] op_sel_hi:[1,0]
	v_pk_mul_f32 v[10:11], v[10:11], v[150:151] op_sel_hi:[1,0]
	v_pk_mul_f32 v[8:9], v[8:9], v[150:151] op_sel_hi:[1,0]
	v_pk_mul_f32 v[6:7], v[6:7], v[150:151] op_sel_hi:[1,0]
	v_pk_mul_f32 v[4:5], v[4:5], v[150:151] op_sel_hi:[1,0]
	v_pk_mul_f32 v[2:3], v[2:3], v[150:151] op_sel_hi:[1,0]
	v_pk_mul_f32 v[0:1], v[0:1], v[150:151] op_sel_hi:[1,0]
	v_pk_mul_f32 v[30:31], v[30:31], v[150:151] op_sel_hi:[1,0]
	v_pk_mul_f32 v[28:29], v[28:29], v[150:151] op_sel_hi:[1,0]
	v_pk_mul_f32 v[26:27], v[26:27], v[150:151] op_sel_hi:[1,0]
	v_pk_mul_f32 v[24:25], v[24:25], v[150:151] op_sel_hi:[1,0]
	v_pk_mul_f32 v[22:23], v[22:23], v[150:151] op_sel_hi:[1,0]
	v_pk_mul_f32 v[20:21], v[20:21], v[150:151] op_sel_hi:[1,0]
	v_pk_mul_f32 v[18:19], v[18:19], v[150:151] op_sel_hi:[1,0]
	v_pk_mul_f32 v[16:17], v[16:17], v[150:151] op_sel_hi:[1,0]
	v_pk_mul_f32 v[46:47], v[46:47], v[150:151] op_sel_hi:[1,0]
	v_pk_mul_f32 v[44:45], v[44:45], v[150:151] op_sel_hi:[1,0]
	v_pk_mul_f32 v[42:43], v[42:43], v[150:151] op_sel_hi:[1,0]
	v_pk_mul_f32 v[40:41], v[40:41], v[150:151] op_sel_hi:[1,0]
	v_pk_mul_f32 v[38:39], v[38:39], v[150:151] op_sel_hi:[1,0]
	v_pk_mul_f32 v[36:37], v[36:37], v[150:151] op_sel_hi:[1,0]
	v_pk_mul_f32 v[34:35], v[34:35], v[150:151] op_sel_hi:[1,0]
	v_pk_mul_f32 v[32:33], v[32:33], v[150:151] op_sel_hi:[1,0]
	v_pk_mul_f32 v[62:63], v[62:63], v[150:151] op_sel_hi:[1,0]
	v_pk_mul_f32 v[60:61], v[60:61], v[150:151] op_sel_hi:[1,0]
	v_pk_mul_f32 v[58:59], v[58:59], v[150:151] op_sel_hi:[1,0]
	v_pk_mul_f32 v[56:57], v[56:57], v[150:151] op_sel_hi:[1,0]
	v_pk_mul_f32 v[54:55], v[54:55], v[150:151] op_sel_hi:[1,0]
	v_pk_mul_f32 v[52:53], v[52:53], v[150:151] op_sel_hi:[1,0]
	v_pk_mul_f32 v[50:51], v[50:51], v[150:151] op_sel_hi:[1,0]
	v_pk_mul_f32 v[48:49], v[48:49], v[150:151] op_sel_hi:[1,0]
	v_pk_add_f32 v[80:81], v[80:81], v[146:147] op_sel_hi:[1,0] neg_lo:[0,1] neg_hi:[0,1]
	v_pk_add_f32 v[96:97], v[96:97], v[146:147] op_sel_hi:[1,0] neg_lo:[0,1] neg_hi:[0,1]
	v_pk_add_f32 v[82:83], v[82:83], v[146:147] op_sel_hi:[1,0] neg_lo:[0,1] neg_hi:[0,1]
	v_pk_add_f32 v[98:99], v[98:99], v[146:147] op_sel_hi:[1,0] neg_lo:[0,1] neg_hi:[0,1]
	v_pk_add_f32 v[84:85], v[84:85], v[146:147] op_sel_hi:[1,0] neg_lo:[0,1] neg_hi:[0,1]
	v_pk_add_f32 v[100:101], v[100:101], v[146:147] op_sel_hi:[1,0] neg_lo:[0,1] neg_hi:[0,1]
	v_pk_add_f32 v[86:87], v[86:87], v[146:147] op_sel_hi:[1,0] neg_lo:[0,1] neg_hi:[0,1]
	v_pk_add_f32 v[102:103], v[102:103], v[146:147] op_sel_hi:[1,0] neg_lo:[0,1] neg_hi:[0,1]
	v_pk_add_f32 v[88:89], v[88:89], v[146:147] op_sel_hi:[1,0] neg_lo:[0,1] neg_hi:[0,1]
	v_pk_add_f32 v[104:105], v[104:105], v[146:147] op_sel_hi:[1,0] neg_lo:[0,1] neg_hi:[0,1]
	v_pk_add_f32 v[90:91], v[90:91], v[146:147] op_sel_hi:[1,0] neg_lo:[0,1] neg_hi:[0,1]
	v_pk_add_f32 v[106:107], v[106:107], v[146:147] op_sel_hi:[1,0] neg_lo:[0,1] neg_hi:[0,1]
	v_pk_add_f32 v[92:93], v[92:93], v[146:147] op_sel_hi:[1,0] neg_lo:[0,1] neg_hi:[0,1]
	v_pk_add_f32 v[108:109], v[108:109], v[146:147] op_sel_hi:[1,0] neg_lo:[0,1] neg_hi:[0,1]
	v_pk_add_f32 v[94:95], v[94:95], v[146:147] op_sel_hi:[1,0] neg_lo:[0,1] neg_hi:[0,1]
	v_pk_add_f32 v[110:111], v[110:111], v[146:147] op_sel_hi:[1,0] neg_lo:[0,1] neg_hi:[0,1]
